# grid barrier: the three LDS state reads issued together (one wait) + GEMM hoisted loads issued as soon as their address is ready
# baseline (speedup 1.0000x reference)
.LBB0_850:
	s_waitcnt vmcnt(0)
	v_mov_b32_e32 v0, v222
	s_waitcnt vmcnt(63) expcnt(7) lgkmcnt(15)
	s_barrier
	s_nop 0
	v_cmp_eq_u32_e32 vcc, 0, v0
	s_and_saveexec_b64 s[0:1], vcc
	s_cbranch_execz .LBB0_897
	s_mov_b64 s[2:3], src_shared_base
	s_waitcnt vmcnt(0) lgkmcnt(0)
	v_mov_b32_e32 v213, s3
	v_mov_b32_e32 v215, s3
	v_mov_b32_e32 v211, s3
	flat_load_dword v6, v[212:213] sc0 sc1
	flat_load_dword v2, v[214:215] sc0 sc1
	flat_load_dword v0, v[210:211] sc0 sc1
	s_waitcnt vmcnt(0) lgkmcnt(0)
	v_lshlrev_b32_e32 v3, 6, v0
	v_add_u32_e32 v0, 0x400, v3
	v_lshl_add_u64 v[4:5], v[0:1], 2, s[22:23]
	v_mov_b32_e32 v0, 1
	global_atomic_add v0, v[4:5], v0, off sc0
	v_cvt_f32_u32_e32 v4, v6
	v_sub_u32_e32 v5, 0, v6
	v_rcp_iflag_f32_e32 v4, v4
	s_nop 0
	v_mul_f32_e32 v4, 0x4f7ffffe, v4
	v_cvt_u32_f32_e32 v4, v4
	v_mul_lo_u32 v5, v5, v4
	v_mul_hi_u32 v5, v4, v5
	v_add_u32_e32 v4, v4, v5
	s_waitcnt vmcnt(0)
	v_mul_hi_u32 v4, v0, v4
	v_mul_lo_u32 v5, v4, v6
	v_sub_u32_e32 v5, v0, v5
	v_cmp_ge_u32_e32 vcc, v5, v6
	v_add_u32_e32 v7, 1, v4
	v_add_u32_e32 v0, 1, v0
	v_cndmask_b32_e32 v4, v4, v7, vcc
	v_sub_u32_e32 v7, v5, v6
	v_cndmask_b32_e32 v5, v5, v7, vcc
	v_cmp_ge_u32_e32 vcc, v5, v6
	v_add_u32_e32 v5, 1, v4
	s_nop 0
	v_cndmask_b32_e32 v4, v4, v5, vcc
	v_mad_u64_u32 v[6:7], s[2:3], v6, v4, v[6:7]
	v_cmp_ne_u32_e32 vcc, v0, v6
	v_add_u32_e32 v0, 0x800, v3
	s_and_saveexec_b64 s[2:3], vcc
	s_xor_b64 s[2:3], exec, s[2:3]
	s_cbranch_execz .LBB0_870
	v_lshl_add_u64 v[2:3], v[0:1], 2, s[22:23]
	global_load_dword v0, v[2:3], off sc1
	s_waitcnt vmcnt(0)
	v_cmp_eq_u32_e32 vcc, v0, v4
	s_and_saveexec_b64 s[4:5], vcc
	s_cbranch_execz .LBB0_869
	s_mov_b32 s26, 0xfffff8
	s_mov_b64 s[6:7], 0
	s_branch .LBB0_861
